# diff+dilated attention: K and V tile loads both issued at the top of a tile iteration and staged to LDS at its end (a full tile of latency cover)
# speedup vs baseline: 1.0229x; 1.0072x over previous
; #define LAS __attribute__((address_space(3)))
; #define AT_GLOADK(kt) do { const size_t r_ = rowbase + (size_t)(kt) * 64; \
;         kreg = *(const u32x4*)(Kp + (r_ + lane) * kpitch + wave * 8); \
;         if (MODE == 0 && wave < 4) kreg2 = *(const u32x4*)(proj + (r_ + lane) * NPROJ + 1920 + wave * 8); } while (0)
; #define AT_GLOADV(kt) do { const size_t r_ = rowbase + (size_t)(kt) * 64; \
;         vreg = *(const u32x4*)(Vp + (r_ + 16 * (wave & 3) + (lane >> 2)) * vpitch + (wave >> 2) * 32 + (lane & 3) * 8); } while (0)
; #define AT_LSTOREK(buf) do { LAS unsigned char* d_ = lds + (buf) * AT_BUF; \
;         *(LAS u32x4*)(d_ + wave * 1024 + lane * 16) = kreg; \
;         if (MODE == 0 && wave < 4) *(LAS u32x4*)(d_ + (8 + wave) * 1024 + lane * 16) = kreg2; } while (0)
; #define AT_LSTOREV(buf) do { LAS unsigned char* d_ = lds + (buf) * AT_BUF; \
;         *(LAS u32x4*)(d_ + AT_V + wave * 1024 + lane * 16) = vreg; } while (0)
; template <int MODE, int NQ>
; __device__ __forceinline__ void attn_unit(LAS unsigned char* lds, const Params& P, int layer, int b, int h, int qb) {
;     ...
;     for (int it = 0; it < NT; ++it) {
;         const int kt = AT_TILE(it);
;         const int bnx = (bcur == 2) ? 0 : bcur + 1, bn2 = (bnx == 2) ? 0 : bnx + 1;
;         const LAS unsigned char* cur = lds + bcur * AT_BUF;
;         const LAS unsigned char* nxt = lds + bnx * AT_BUF;
; #pragma unroll
;         for (int hf = 0; hf < 2; ++hf) {
;             if (it + 2 < NT) { if (hf == 0) AT_GLOADK(AT_TILE(it + 2)); else AT_GLOADV(AT_TILE(it + 2)); }
;     ...
;             if (it + 2 < NT) { if (hf == 0) AT_LSTOREK(bn2); else AT_LSTOREV(bn2); }
;         }
;         __syncthreads();
;         bcur = bnx;
.LBB0_409:
	s_addk_i32 s8, 0x100
	s_add_i32 s7, s7, 1
	s_cmpk_eq_i32 s8, 0x1e00
	s_waitcnt vmcnt(0)
	ds_write_b128 v202, v[2:5]
	ds_write_b128 v202, v[224:227] offset:12288
	s_waitcnt lgkmcnt(0)
	s_barrier
	s_cbranch_scc1 .LBB0_434
.LBB0_410:
	s_mul_i32 s10, s9, 0x5000
	s_add_i32 s16, s10, 0
	s_add_i32 s10, s5, s8
	s_add_i32 s11, s10, 0xffffe000
	s_cmp_gt_u32 s7, 31
	v_add3_u32 v0, s16, v193, v192
	s_cselect_b32 s10, s11, s10
	v_add_u32_e32 v199, v0, v189
	v_add_u32_e32 v0, s10, v191
	s_add_i32 s10, s7, 2
	s_sub_i32 s11, s7, 30
	s_cmp_gt_u32 s10, 31
	s_cselect_b32 s10, s11, s10
	s_ashr_i32 s11, s10, 31
	s_lshl_b64 s[10:11], s[10:11], 6
	v_lshl_add_u64 v[2:3], v[182:183], 0, s[10:11]
	v_mov_b64_e32 v[4:5], s[0:1]
	v_mad_u64_u32 v[4:5], s[14:15], v2, s27, v[4:5]
	v_mad_i32_i24 v5, v3, s27, v5
	global_load_dwordx4 v[2:5], v[4:5], off
	v_lshl_add_u64 v[228:229], v[178:179], 0, s[10:11]
	v_mad_u64_u32 v[230:231], s[14:15], v228, s27, v[180:181]
	v_mad_i32_i24 v231, v229, s27, v231
	global_load_dwordx4 v[224:227], v[230:231], off
	s_waitcnt lgkmcnt(3)
	v_mfma_f32_32x32x16_bf16 v[96:111], v[140:143], v[124:127], 0
	s_waitcnt lgkmcnt(1)
	v_mfma_f32_32x32x16_bf16 v[80:95], v[132:135], v[120:123], 0
	v_mfma_f32_32x32x16_bf16 v[96:111], v[136:139], v[116:119], v[96:111]
	s_waitcnt lgkmcnt(0)
	v_mfma_f32_32x32x16_bf16 v[80:95], v[128:131], v[112:115], v[80:95]
	ds_read_b64_tr_b16 v[148:149], v199 offset:12288
	ds_read_b64_tr_b16 v[150:151], v199 offset:12800
	ds_read_b64_tr_b16 v[144:145], v199 offset:13312
	ds_read_b64_tr_b16 v[146:147], v199 offset:13824
	ds_read_b64_tr_b16 v[140:141], v199 offset:16384
	ds_read_b64_tr_b16 v[142:143], v199 offset:16896
	ds_read_b64_tr_b16 v[136:137], v199 offset:17408
	ds_read_b64_tr_b16 v[138:139], v199 offset:17920
	v_add3_u32 v6, s16, v195, v196
	ds_read_b128 v[132:135], v6 offset:512
	ds_read_b128 v[128:131], v6 offset:2560
	ds_read_b128 v[10:13], v6 offset:4608
	ds_read_b128 v[6:9], v6 offset:6656
	ds_read_b128 v[156:159], v0 offset:61440
	ds_read_b128 v[152:155], v0 offset:61472
	ds_read_b128 v[164:167], v0 offset:61504
	ds_read_b128 v[172:175], v0 offset:61536
	s_waitcnt lgkmcnt(3)
	v_pk_fma_f32 v[160:161], v[96:97], s[34:35], v[156:157] op_sel_hi:[1,0,1]
	v_pk_fma_f32 v[98:99], v[98:99], s[34:35], v[158:159] op_sel_hi:[1,0,1]
	v_max3_f32 v96, v160, s68, v161
	s_waitcnt lgkmcnt(2)
	v_pk_fma_f32 v[14:15], v[100:101], s[34:35], v[152:153] op_sel_hi:[1,0,1]
	v_max3_f32 v96, v96, v98, v99
	v_max3_f32 v100, v96, v14, v15
	v_pk_fma_f32 v[96:97], v[102:103], s[34:35], v[154:155] op_sel_hi:[1,0,1]
	s_waitcnt lgkmcnt(1)
	v_pk_fma_f32 v[104:105], v[104:105], s[34:35], v[164:165] op_sel_hi:[1,0,1]
	v_max3_f32 v100, v100, v96, v97
	v_max3_f32 v102, v100, v104, v105
	v_pk_fma_f32 v[100:101], v[106:107], s[34:35], v[166:167] op_sel_hi:[1,0,1]
	s_nop 0
	v_max3_f32 v106, v102, v100, v101
	s_waitcnt lgkmcnt(0)
	v_pk_fma_f32 v[102:103], v[108:109], s[34:35], v[172:173] op_sel_hi:[1,0,1]
	s_nop 0
	v_max3_f32 v108, v106, v102, v103
	v_pk_fma_f32 v[106:107], v[110:111], s[34:35], v[174:175] op_sel_hi:[1,0,1]
	s_nop 0
	v_max3_f32 v108, v108, v106, v107
	v_mov_b32_e32 v109, v108
	s_nop 1
	v_permlane32_swap_b32_e32 v108, v109
	v_max_f32_e32 v108, v108, v109
	v_max_f32_e32 v200, v198, v108
	v_add_f32_e32 v109, 0x41000000, v198
	v_cmp_gt_f32_e32 vcc, v200, v109
	s_cbranch_vccz .LBB0_412
	v_sub_f32_e32 v109, v198, v200
	s_mov_b32 s61, 0
	v_exp_f32_e32 v110, v109
	s_nop 0
	v_mul_f32_e32 v188, v188, v110
	v_pk_mul_f32 v[78:79], v[78:79], v[110:111] op_sel_hi:[1,0]
	v_pk_mul_f32 v[76:77], v[76:77], v[110:111] op_sel_hi:[1,0]
	v_pk_mul_f32 v[74:75], v[74:75], v[110:111] op_sel_hi:[1,0]
	v_pk_mul_f32 v[72:73], v[72:73], v[110:111] op_sel_hi:[1,0]
	v_pk_mul_f32 v[70:71], v[70:71], v[110:111] op_sel_hi:[1,0]
	v_pk_mul_f32 v[68:69], v[68:69], v[110:111] op_sel_hi:[1,0]
	v_pk_mul_f32 v[66:67], v[66:67], v[110:111] op_sel_hi:[1,0]
	v_pk_mul_f32 v[64:65], v[64:65], v[110:111] op_sel_hi:[1,0]
	v_pk_mul_f32 v[30:31], v[30:31], v[110:111] op_sel_hi:[1,0]
	v_pk_mul_f32 v[28:29], v[28:29], v[110:111] op_sel_hi:[1,0]
	v_pk_mul_f32 v[26:27], v[26:27], v[110:111] op_sel_hi:[1,0]
	v_pk_mul_f32 v[24:25], v[24:25], v[110:111] op_sel_hi:[1,0]
	v_pk_mul_f32 v[22:23], v[22:23], v[110:111] op_sel_hi:[1,0]
	v_pk_mul_f32 v[20:21], v[20:21], v[110:111] op_sel_hi:[1,0]
	v_pk_mul_f32 v[18:19], v[18:19], v[110:111] op_sel_hi:[1,0]
	v_pk_mul_f32 v[16:17], v[16:17], v[110:111] op_sel_hi:[1,0]
	s_branch .LBB0_413

; template <int MODE, int NQ>
; __device__ __forceinline__ void attn_unit(LAS unsigned char* lds, const Params& P, int layer, int b, int h, int qb) {
;     ...
;         const int bnx = (bcur == 2) ? 0 : bcur + 1, bn2 = (bnx == 2) ? 0 : bnx + 1;
;         const LAS unsigned char* cur = lds + bcur * AT_BUF;
;         const LAS unsigned char* nxt = lds + bnx * AT_BUF;
; #pragma unroll
;         for (int hf = 0; hf < 2; ++hf) {
;             if (it + 2 < NT) { if (hf == 0) AT_GLOADK(AT_TILE(it + 2)); else AT_GLOADV(AT_TILE(it + 2)); }
;             f32x16 sc[NC];
; #pragma unroll
;             for (int cc = 0; cc < NC; ++cc) {
;                 sc[cc] = f32x16{};
; #pragma unroll
;                 for (int d0 = 0; d0 < ND0; ++d0) sc[cc] = __builtin_amdgcn_mfma_f32_32x32x16_bf16(kf[(cc % NMAP) * ND0 + d0], qf[cc][d0], sc[cc], 0, 0, 0);
;             }
;             __builtin_amdgcn_sched_barrier(0);
;             AT_VLOAD(cur, hf);
;             if (hf == 0) AT_KLOAD(cur, 1); else if (it + 1 < NT) AT_KLOAD(nxt, 0);
;             __builtin_amdgcn_sched_barrier(0);
;             bf16x8 pw[NC][2]; float rmrel[NC]; bool alive = false;
; #pragma unroll
;             for (int cc = 0; cc < NC; ++cc) {
;                 f32x16& s0 = sc[cc];
;                 float mn;
;                 if (MODE != 0) {
;                     const LAS f32x4* tp4 = (const LAS f32x4*)(tlane + (kt * 64 + hf * 32) * 4);
;                     float rm = -3e38f;
; #pragma unroll
;                     for (int g = 0; g < 4; ++g) { const f32x4 t4 = tp4[2 * g];
; #pragma unroll
;                         for (int i = 0; i < 4; ++i) { s0[4 * g + i] = s0[4 * g + i] * c + t4[i]; rm = fmaxf(rm, s0[4 * g + i]); } }
;                     rm = xmax(rm);
;                     mn = fmaxf(mrun[cc], rm);
;                     rmrel[cc] = rm;
;                 } else {
;                     float rm = -3e38f;
; #pragma unroll
;                     for (int r = 0; r < 16; ++r) rm = fmaxf(rm, s0[r]);
;                     rm = xmax(rm);
;                     mn = fmaxf(mrun[cc], rm * c);
;                 }
;                 if (__any(mn > mrun[cc] + AT_THR)) {
;                     const float al = fast_exp2(mrun[cc] - mn); lrun[cc] *= al;
; #pragma unroll
;                     for (int r = 0; r < 16; ++r) { o[cc][0][r] *= al; o[cc][1][r] *= al; }
;                     mrun[cc] = mn;
;                 }
.LBB0_422:
	s_add_i32 s14, s9, 1
	s_cmp_lg_u32 s9, 2
	s_cselect_b32 s9, s14, 0
	s_mul_i32 s15, s9, 0x5000
	s_add_i32 s10, s15, 0x5000
	s_cmp_lg_u32 s9, 2
	s_cselect_b32 s14, s10, 0
	v_add_u32_e32 v202, s14, v194
	v_mfma_f32_32x32x16_bf16 v[96:111], v[132:135], v[124:127], 0
	v_mfma_f32_32x32x16_bf16 v[80:95], v[10:13], v[120:123], 0
	v_mfma_f32_32x32x16_bf16 v[96:111], v[128:131], v[116:119], v[96:111]
	v_mfma_f32_32x32x16_bf16 v[80:95], v[6:9], v[112:115], v[80:95]
	ds_read_b64_tr_b16 v[148:149], v199 offset:14336
	ds_read_b64_tr_b16 v[150:151], v199 offset:14848
	ds_read_b64_tr_b16 v[144:145], v199 offset:15360
	ds_read_b64_tr_b16 v[146:147], v199 offset:15872
	ds_read_b64_tr_b16 v[10:11], v199 offset:18432
	ds_read_b64_tr_b16 v[12:13], v199 offset:18944
	ds_read_b64_tr_b16 v[6:7], v199 offset:19456
	ds_read_b64_tr_b16 v[8:9], v199 offset:19968
	v_add_u32_e32 v14, s15, v190
	ds_read_b128 v[140:143], v14
	ds_read_b128 v[136:139], v14 offset:2048
	ds_read_b128 v[132:135], v14 offset:4096
	ds_read_b128 v[128:131], v14 offset:6144
	ds_read_b128 v[156:159], v0 offset:61568
	ds_read_b128 v[152:155], v0 offset:61600
	ds_read_b128 v[164:167], v0 offset:61632
	ds_read_b128 v[172:175], v0 offset:61664
	s_waitcnt lgkmcnt(3)
	v_pk_fma_f32 v[160:161], v[96:97], s[34:35], v[156:157] op_sel_hi:[1,0,1]
	v_pk_fma_f32 v[98:99], v[98:99], s[34:35], v[158:159] op_sel_hi:[1,0,1]
	v_max3_f32 v96, v160, s68, v161
	s_waitcnt lgkmcnt(2)
	v_pk_fma_f32 v[14:15], v[100:101], s[34:35], v[152:153] op_sel_hi:[1,0,1]
	v_max3_f32 v96, v96, v98, v99
	v_max3_f32 v100, v96, v14, v15
	v_pk_fma_f32 v[96:97], v[102:103], s[34:35], v[154:155] op_sel_hi:[1,0,1]
	s_waitcnt lgkmcnt(1)
	v_pk_fma_f32 v[104:105], v[104:105], s[34:35], v[164:165] op_sel_hi:[1,0,1]
	v_max3_f32 v100, v100, v96, v97
	v_max3_f32 v0, v100, v104, v105
	v_pk_fma_f32 v[100:101], v[106:107], s[34:35], v[166:167] op_sel_hi:[1,0,1]
	s_waitcnt lgkmcnt(0)
	v_pk_fma_f32 v[102:103], v[108:109], s[34:35], v[172:173] op_sel_hi:[1,0,1]
	v_max3_f32 v0, v0, v100, v101
	v_max3_f32 v0, v0, v102, v103
	v_pk_fma_f32 v[106:107], v[110:111], s[34:35], v[174:175] op_sel_hi:[1,0,1]
	s_nop 0
	v_max3_f32 v0, v0, v106, v107
	v_mov_b32_e32 v108, v0
	s_nop 1
	v_permlane32_swap_b32_e32 v0, v108
	v_max_f32_e32 v0, v0, v108
	v_max_f32_e32 v198, v200, v0
	v_add_f32_e32 v108, 0x41000000, v200
	v_cmp_gt_f32_e32 vcc, v198, v108
	s_cbranch_vccz .LBB0_424
	v_sub_f32_e32 v108, v200, v198
	s_mov_b32 s61, 0
	v_exp_f32_e32 v108, v108
	s_nop 0
	v_mul_f32_e32 v188, v188, v108
	v_pk_mul_f32 v[78:79], v[78:79], v[108:109] op_sel_hi:[1,0]
	v_pk_mul_f32 v[76:77], v[76:77], v[108:109] op_sel_hi:[1,0]
	v_pk_mul_f32 v[74:75], v[74:75], v[108:109] op_sel_hi:[1,0]
	v_pk_mul_f32 v[72:73], v[72:73], v[108:109] op_sel_hi:[1,0]
	v_pk_mul_f32 v[70:71], v[70:71], v[108:109] op_sel_hi:[1,0]
	v_pk_mul_f32 v[68:69], v[68:69], v[108:109] op_sel_hi:[1,0]
	v_pk_mul_f32 v[66:67], v[66:67], v[108:109] op_sel_hi:[1,0]
	v_pk_mul_f32 v[64:65], v[64:65], v[108:109] op_sel_hi:[1,0]
	v_pk_mul_f32 v[30:31], v[30:31], v[108:109] op_sel_hi:[1,0]
	v_pk_mul_f32 v[28:29], v[28:29], v[108:109] op_sel_hi:[1,0]
	v_pk_mul_f32 v[26:27], v[26:27], v[108:109] op_sel_hi:[1,0]
	v_pk_mul_f32 v[24:25], v[24:25], v[108:109] op_sel_hi:[1,0]
	v_pk_mul_f32 v[22:23], v[22:23], v[108:109] op_sel_hi:[1,0]
	v_pk_mul_f32 v[20:21], v[20:21], v[108:109] op_sel_hi:[1,0]
	v_pk_mul_f32 v[18:19], v[18:19], v[108:109] op_sel_hi:[1,0]
	v_pk_mul_f32 v[16:17], v[16:17], v[108:109] op_sel_hi:[1,0]
	s_branch .LBB0_425

; #define LAS __attribute__((address_space(3)))
; #define AT_GLOADK(kt) do { const size_t r_ = rowbase + (size_t)(kt) * 64; \
;         kreg = *(const u32x4*)(Kp + (r_ + lane) * kpitch + wave * 8); \
;         if (MODE == 0 && wave < 4) kreg2 = *(const u32x4*)(proj + (r_ + lane) * NPROJ + 1920 + wave * 8); } while (0)
; #define AT_GLOADV(kt) do { const size_t r_ = rowbase + (size_t)(kt) * 64; \
;         vreg = *(const u32x4*)(Vp + (r_ + 16 * (wave & 3) + (lane >> 2)) * vpitch + (wave >> 2) * 32 + (lane & 3) * 8); } while (0)
; template <int MODE, int NQ>
; __device__ __forceinline__ void attn_unit(LAS unsigned char* lds, const Params& P, int layer, int b, int h, int qb) {
;     ...
;     for (int it = 0; it < NT; ++it) {
;         const int kt = AT_TILE(it);
;         const int bnx = (bcur == 2) ? 0 : bcur + 1, bn2 = (bnx == 2) ? 0 : bnx + 1;
;         const LAS unsigned char* cur = lds + bcur * AT_BUF;
;         const LAS unsigned char* nxt = lds + bnx * AT_BUF;
; #pragma unroll
;         for (int hf = 0; hf < 2; ++hf) {
;             if (it + 2 < NT) { if (hf == 0) AT_GLOADK(AT_TILE(it + 2)); else AT_GLOADV(AT_TILE(it + 2)); }
.LBB0_503:
	s_add_i32 s16, s8, s18
	s_cmp_lt_u32 s18, s6
	s_cselect_b64 s[10:11], -1, 0
	s_cmp_ge_i32 s16, s6
	s_cselect_b32 s14, s6, 0
	s_add_i32 s15, s7, s18
	s_sub_i32 s14, s15, s14
	s_ashr_i32 s15, s14, 31
	s_lshl_b64 s[14:15], s[14:15], 6
	s_cmp_ge_u32 s18, s6
	s_cbranch_scc1 .LBB0_505
	v_lshl_add_u64 v[2:3], v[122:123], 0, s[14:15]
	v_mov_b64_e32 v[4:5], s[0:1]
	v_mad_u64_u32 v[4:5], s[20:21], v2, s27, v[4:5]
	v_mad_i32_i24 v5, v3, s27, v5
	global_load_dwordx4 v[80:83], v[4:5], off
	v_lshl_add_u64 v[2:3], v[118:119], 0, s[14:15]
	v_mad_u64_u32 v[4:5], s[20:21], v2, s27, v[120:121]
	v_mad_i32_i24 v5, v3, s27, v5
	global_load_dwordx4 v[84:87], v[4:5], off

; #define LAS __attribute__((address_space(3)))
; #define AT_GLOADK(kt) do { const size_t r_ = rowbase + (size_t)(kt) * 64; \
;         kreg = *(const u32x4*)(Kp + (r_ + lane) * kpitch + wave * 8); \
;         if (MODE == 0 && wave < 4) kreg2 = *(const u32x4*)(proj + (r_ + lane) * NPROJ + 1920 + wave * 8); } while (0)
; #define AT_GLOADV(kt) do { const size_t r_ = rowbase + (size_t)(kt) * 64; \
;         vreg = *(const u32x4*)(Vp + (r_ + 16 * (wave & 3) + (lane >> 2)) * vpitch + (wave >> 2) * 32 + (lane & 3) * 8); } while (0)
; #define AT_KLOAD(bufbase, hf) do { _Pragma("unroll") for (int j_ = 0; j_ < NK; ++j_) kf[j_] = *(const LAS bf16x8*)((bufbase) + (2 * j_ + hi) * 1024 + (hf) * 512 + r32 * 16); } while (0)
; #define AT_VLOAD(bufbase, hf) do { _Pragma("unroll") for (int dv_ = 0; dv_ < 2; ++dv_) _Pragma("unroll") for (int k2_ = 0; k2_ < 2; ++k2_) { \
;         vlo[dv_ * 2 + k2_] = vtr((bufbase) + AT_V + vlane + dv_ * 4096 + (2 * (hf) + k2_) * 1024); vhi[dv_ * 2 + k2_] = vtr((bufbase) + AT_V + vlane + dv_ * 4096 + (2 * (hf) + k2_) * 1024 + 512); } } while (0)
; template <int MODE, int NQ>
; __device__ __forceinline__ void attn_unit(LAS unsigned char* lds, const Params& P, int layer, int b, int h, int qb) {
;     ...
;         const int bnx = (bcur == 2) ? 0 : bcur + 1, bn2 = (bnx == 2) ? 0 : bnx + 1;
;         const LAS unsigned char* cur = lds + bcur * AT_BUF;
;         const LAS unsigned char* nxt = lds + bnx * AT_BUF;
; #pragma unroll
;         for (int hf = 0; hf < 2; ++hf) {
;             if (it + 2 < NT) { if (hf == 0) AT_GLOADK(AT_TILE(it + 2)); else AT_GLOADV(AT_TILE(it + 2)); }
;             f32x16 sc[NC];
; #pragma unroll
;             for (int cc = 0; cc < NC; ++cc) {
;                 sc[cc] = f32x16{};
; #pragma unroll
;                 for (int d0 = 0; d0 < ND0; ++d0) sc[cc] = __builtin_amdgcn_mfma_f32_32x32x16_bf16(kf[(cc % NMAP) * ND0 + d0], qf[cc][d0], sc[cc], 0, 0, 0);
;             }
;             __builtin_amdgcn_sched_barrier(0);
;             AT_VLOAD(cur, hf);
;             if (hf == 0) AT_KLOAD(cur, 1); else if (it + 1 < NT) AT_KLOAD(nxt, 0);
.LBB0_512:
	s_add_i32 s16, s19, 1
	s_cmp_lg_u32 s19, 2
	s_cselect_b32 s19, s16, 0
	s_mul_i32 s16, s19, 0x5000
	s_add_i32 s17, s16, 0x5000
	s_cmp_lg_u32 s19, 2
	s_cselect_b32 s17, s17, 0
	v_cndmask_b32_e64 v2, 0, 1, s[10:11]
	v_cmp_ne_u32_e64 s[42:43], 1, v2
	s_andn2_b64 vcc, exec, s[10:11]
	v_add_u32_e32 v14, s17, v125
	s_cbranch_vccnz .LBB0_514
.LBB0_514:
	s_add_i32 s14, s18, -1
	s_cmp_ge_u32 s14, s6
	v_mfma_f32_32x32x16_bf16 v[48:63], v[96:99], v[64:67], 0
	ds_read_b64_tr_b16 v[2:3], v15 offset:14336
	ds_read_b64_tr_b16 v[4:5], v15 offset:14848
	ds_read_b64_tr_b16 v[6:7], v15 offset:15360
	ds_read_b64_tr_b16 v[8:9], v15 offset:15872
	ds_read_b64_tr_b16 v[10:11], v15 offset:18432
	ds_read_b64_tr_b16 v[12:13], v15 offset:18944
	ds_read_b64_tr_b16 v[104:105], v15 offset:19456
	ds_read_b64_tr_b16 v[106:107], v15 offset:19968
	v_mfma_f32_32x32x16_bf16 v[48:63], v[100:103], v[68:71], v[48:63]
	v_mfma_f32_32x32x16_bf16 v[48:63], v[92:95], v[72:75], v[48:63]
	v_mfma_f32_32x32x16_bf16 v[48:63], v[88:91], v[76:79], v[48:63]
	s_cbranch_scc1 .LBB0_516
	v_add_u32_e32 v15, s16, v128
	ds_read_b128 v[96:99], v15
	ds_read_b128 v[100:103], v15 offset:2048
	ds_read_b128 v[92:95], v15 offset:4096
	ds_read_b128 v[88:91], v15 offset:6144

; #define AT_LSTOREK(buf) do { LAS unsigned char* d_ = lds + (buf) * AT_BUF; \
;         *(LAS u32x4*)(d_ + wave * 1024 + lane * 16) = kreg; \
;         if (MODE == 0 && wave < 4) *(LAS u32x4*)(d_ + (8 + wave) * 1024 + lane * 16) = kreg2; } while (0)
; #define AT_LSTOREV(buf) do { LAS unsigned char* d_ = lds + (buf) * AT_BUF; \
;         *(LAS u32x4*)(d_ + AT_V + wave * 1024 + lane * 16) = vreg; } while (0)
; template <int MODE, int NQ>
; __device__ __forceinline__ void attn_unit(LAS unsigned char* lds, const Params& P, int layer, int b, int h, int qb) {
;     ...
;             if (it + 2 < NT) { if (hf == 0) AT_LSTOREK(bn2); else AT_LSTOREV(bn2); }
;         }
;         __syncthreads();
;         bcur = bnx;
.LBB0_523:
	s_and_b64 vcc, exec, s[42:43]
	s_cbranch_vccnz .LBB0_502
	s_waitcnt vmcnt(0)
	ds_write_b128 v14, v[80:83]
	ds_write_b128 v14, v[84:87] offset:12288
	s_branch .LBB0_502
